# GLA loop: chunk-B flush point no longer waits for its own flush-store acks (vmcnt(0) -> counted vmcnt(11) for the decay scalars; chunk-A prefetch waited at the back-edge with vmcnt(11); tail paths dra
# baseline (speedup 1.0000x reference)
; __device__ __forceinline__ void gla_unit(const Params& p, const WS& ws, int u, bool dry = false) {
;     ...
;   auto body = [&](int c, u32x4 (&qr)[4], u32x4 (&kr)[4], u32x4& vr, float (&ebl)[2]) {
; #pragma unroll
;     for (int i = 0; i < 4; ++i) {
;       const int ci = tid + 256 * i; const int row = ci >> 4, ch = ci & 15;
;       *(u32x4*)(QDs + row * 136 + ch * 8) = qr[i];
;       *(u32x4*)(KIs + row * 136 + ch * 8) = kr[i];
;       const unsigned kk[4] = {kr[i].x, kr[i].y, kr[i].z, kr[i].w};
; #pragma unroll
;       for (int e = 0; e < 4; ++e) {
;         KIT[(ch * 8 + 2 * e) * 72 + (row ^ ((ch & 7) << 3))] = (bf16_t)(kk[e] & 0xffffu);
;     ...
; #pragma unroll
;     for (int ks = 0; ks < 4; ++ks)
; #pragma unroll
;       for (int mt = 0; mt < 2; ++mt) {
;         const bf16x8 sf = *(const bf16x8*)(STs + (16 * mt + lr) * 136 + 32 * ks + 8 * lq);
;         oacc[mt] = MFMA16(sf, xq[ks], oacc[mt]);
;       }
;     {
;       const int t = 64 * c - 48 + irow;
;       float sq = 0.f;
; #pragma unroll
;       for (int mt = 0; mt < 2; ++mt) sq += oacc[mt][0] * oacc[mt][0] + oacc[mt][1] * oacc[mt][1] + oacc[mt][2] * oacc[mt][2] + oacc[mt][3] * oacc[mt][3];
;       sq += __shfl_xor(sq, 16); sq += __shfl_xor(sq, 32);
;       tpend = t;
;       sqpend = sq;
; #pragma unroll
;       for (int mt = 0; mt < 2; ++mt) { opend[mt].x = cvt_pk_bf16(oacc[mt][0], oacc[mt][1]); opend[mt].y = cvt_pk_bf16(oacc[mt][2], oacc[mt][3]); }
;     }
;     __syncthreads();
; #pragma unroll
;     for (int ntl = 0; ntl < 2; ++ntl) {
; #pragma unroll
;       for (int ks = 0; ks < 2; ++ks) {
;         const bf16x8 kf = *(const bf16x8*)(KIT + (16 * (2 * w + ntl) + lr) * 72 + (((4 * ks + lq) ^ (((16 * (2 * w + ntl) + lr) >> 3) & 7)) << 3));
; #pragma unroll
;         for (int mt = 0; mt < 2; ++mt) {
;           const bf16x8 vf = *(const bf16x8*)(VTs + (16 * mt + lr) * 72 + (((4 * ks + lq) ^ (((16 * mt + lr) >> 3) & 3)) << 3));
;           sacc[mt][ntl] = MFMA16(vf, kf, sacc[mt][ntl]);
;         }
;       }
;       const float e = ntl ? eb1 : eb0;
; #pragma unroll
;       for (int mt = 0; mt < 2; ++mt) {
;         sacc[mt][ntl] = scale4(sacc[mt][ntl], e);
; #pragma unroll
;         for (int jj = 0; jj < 4; ++jj) STs[(16 * mt + 4 * lq + jj) * 136 + 16 * (2 * w + ntl) + lr] = f2bf(sacc[mt][ntl][jj]);
;       }
;     }
;     __syncthreads();
;   };
.LBB0_1634:
	s_or_b64 exec, exec, s[12:13]
	s_nop 1
	s_nop 0
	s_nop 0
	s_cmp_gt_u32 s35, 32
	s_waitcnt lgkmcnt(0)
	v_mfma_f32_16x16x32_bf16 v[108:111], v[212:215], v[104:107], v[116:119]
	s_waitcnt lgkmcnt(0)
	v_mfma_f32_16x16x32_bf16 v[104:107], v[216:219], v[104:107], v[120:123]
	s_nop 0
	s_waitcnt lgkmcnt(0)
	v_mfma_f32_16x16x32_bf16 v[108:111], v[220:223], v[100:103], v[108:111]
	s_nop 0
	s_waitcnt lgkmcnt(0)
	v_mfma_f32_16x16x32_bf16 v[100:103], v[224:227], v[100:103], v[104:107]
	s_nop 2
	s_nop 0
	s_waitcnt lgkmcnt(0)
	v_mfma_f32_16x16x32_bf16 v[104:107], v[228:231], v[8:11], v[108:111]
	s_nop 2
	s_nop 0
	s_waitcnt lgkmcnt(0)
	v_mfma_f32_16x16x32_bf16 v[8:11], v[232:235], v[8:11], v[100:103]
	s_nop 2
	s_nop 0
	s_waitcnt lgkmcnt(0)
	v_mfma_f32_16x16x32_bf16 v[100:103], v[244:247], v[4:7], v[104:107]
	s_nop 2
	s_nop 0
	s_waitcnt lgkmcnt(0)
	s_barrier
	v_mfma_f32_16x16x32_bf16 v[6:9], v[248:251], v[4:7], v[8:11]
	ds_read_b128 v[212:215], v169 offset:34816
	ds_read_b128 v[216:219], v170 offset:53248
	ds_read_b128 v[220:223], v171 offset:53248
	ds_read_b128 v[224:227], v172 offset:34816
	ds_read_b128 v[228:231], v173 offset:53248
	ds_read_b128 v[232:235], v174 offset:53248
	ds_read_b128 v[244:247], v180 offset:34816
	ds_read_b128 v[252:255], v181 offset:34816
	s_nop 2
	v_mov_b32_e32 v10, v101
	v_mov_b32_e32 v4, v100
	s_nop 2
	v_mov_b32_e32 v11, v7
	v_mov_b32_e32 v5, v6
	v_pk_mul_f32 v[10:11], v[10:11], v[10:11]
	v_cvt_pk_bf16_f32 v6, v6, v7
	v_pk_fma_f32 v[4:5], v[4:5], v[4:5], v[10:11]
	v_mov_b32_e32 v10, v102
	v_mov_b32_e32 v11, v8
	v_pk_fma_f32 v[4:5], v[10:11], v[10:11], v[4:5]
	v_mov_b32_e32 v10, v103
	v_mov_b32_e32 v11, v9
	v_pk_fma_f32 v[4:5], v[10:11], v[10:11], v[4:5]
	v_cvt_pk_bf16_f32 v7, v8, v9
	v_add_f32_e32 v4, v4, v5
	ds_bpermute_b32 v5, v163, v4
	v_mov_b32_e32 v8, v208
	s_waitcnt lgkmcnt(0)
	v_add_f32_e32 v4, v4, v5
	ds_bpermute_b32 v5, v168, v4
	s_waitcnt lgkmcnt(0)
	v_add_f32_e32 v10, v4, v5
	v_cvt_pk_bf16_f32 v4, v100, v101
	v_cvt_pk_bf16_f32 v5, v102, v103
	s_nop 0
	s_nop 0
	s_waitcnt lgkmcnt(0)
	v_mfma_f32_16x16x32_bf16 v[84:87], v[216:219], v[212:215], v[84:87]
	s_nop 0
	s_nop 0
	v_mfma_f32_16x16x32_bf16 v[96:99], v[220:223], v[212:215], v[96:99]
	s_nop 0
	s_nop 0
	s_nop 0
	v_mfma_f32_16x16x32_bf16 v[84:87], v[228:231], v[224:227], v[84:87]
	s_nop 0
	s_nop 0
	v_mfma_f32_16x16x32_bf16 v[96:99], v[232:235], v[224:227], v[96:99]
	s_nop 4
	v_mul_f32_e32 v84, v84, v8
	v_mul_f32_e32 v85, v85, v8
	v_mul_f32_e32 v86, v86, v8
	v_mul_f32_e32 v87, v87, v8
	s_nop 0
	v_cvt_pk_bf16_f32 v8, v84, s0
	ds_write_b16 v178, v8 offset:57856
	v_cvt_pk_bf16_f32 v8, v85, s0
	ds_write_b16 v178, v8 offset:58128
	v_cvt_pk_bf16_f32 v8, v86, s0
	ds_write_b16 v178, v8 offset:58400
	v_cvt_pk_bf16_f32 v8, v87, s0
	ds_write_b16 v178, v8 offset:58672
	s_nop 0
	v_mul_f32_e32 v96, v96, v208
	v_mul_f32_e32 v97, v97, v208
	v_mul_f32_e32 v98, v98, v208
	v_mul_f32_e32 v99, v99, v208
	s_nop 0
	v_cvt_pk_bf16_f32 v8, v96, s0
	ds_write_b16 v178, v8 offset:62208
	v_cvt_pk_bf16_f32 v8, v97, s0
	ds_write_b16 v178, v8 offset:62480
	v_cvt_pk_bf16_f32 v8, v98, s0
	ds_write_b16 v178, v8 offset:62752
	v_cvt_pk_bf16_f32 v8, v99, s0
	ds_write_b16 v178, v8 offset:63024
	s_nop 0
	s_nop 0
	s_nop 0
	v_mfma_f32_16x16x32_bf16 v[88:91], v[216:219], v[244:247], v[88:91]
	s_nop 0
	v_mov_b32_e32 v8, v207
	s_nop 0
	v_mfma_f32_16x16x32_bf16 v[92:95], v[220:223], v[244:247], v[92:95]
	s_nop 0
	s_nop 0
	s_nop 0
	v_mfma_f32_16x16x32_bf16 v[88:91], v[228:231], v[252:255], v[88:91]
	s_nop 0
	s_nop 0
	v_mfma_f32_16x16x32_bf16 v[92:95], v[232:235], v[252:255], v[92:95]
	s_nop 4
	v_mul_f32_e32 v88, v88, v8
	v_mul_f32_e32 v89, v89, v8
	v_mul_f32_e32 v90, v90, v8
	v_mul_f32_e32 v91, v91, v8
	s_nop 0
	v_cvt_pk_bf16_f32 v8, v88, s0
	ds_write_b16 v178, v8 offset:57888
	v_cvt_pk_bf16_f32 v8, v89, s0
	ds_write_b16 v178, v8 offset:58160
	v_cvt_pk_bf16_f32 v8, v90, s0
	ds_write_b16 v178, v8 offset:58432
	v_cvt_pk_bf16_f32 v8, v91, s0
	ds_write_b16 v178, v8 offset:58704
	s_nop 0
	v_mul_f32_e32 v92, v92, v207
	v_mul_f32_e32 v93, v93, v207
	v_mul_f32_e32 v94, v94, v207
	v_mul_f32_e32 v95, v95, v207
	s_nop 0
	v_cvt_pk_bf16_f32 v8, v92, s0
	ds_write_b16 v178, v8 offset:62240
	v_cvt_pk_bf16_f32 v8, v93, s0
	ds_write_b16 v178, v8 offset:62512
	v_cvt_pk_bf16_f32 v8, v94, s0
	ds_write_b16 v178, v8 offset:62784
	v_cvt_pk_bf16_f32 v8, v95, s0
	ds_write_b16 v178, v8 offset:63056
	s_waitcnt lgkmcnt(0)
	s_barrier
	s_cbranch_scc1 .LBB0_1663
	v_add_u32_e32 v207, s92, v161
	v_subrev_u32_e32 v8, 48, v207
	v_cmp_lt_i32_e64 s[80:81], -1, v8
	s_waitcnt vmcnt(11)
	ds_write_b128 v147, v[44:47]
	ds_write_b128 v147, v[48:51] offset:17408
	ds_write_b16 v148, v48 offset:34816
	ds_write_b16_d16_hi v149, v48 offset:34960
	ds_write_b16 v148, v49 offset:35104
	ds_write_b16_d16_hi v148, v49 offset:35248
	ds_write_b16 v148, v50 offset:35392
	ds_write_b16_d16_hi v148, v50 offset:35536
	ds_write_b16 v148, v51 offset:35680
	ds_write_b16_d16_hi v148, v51 offset:35824
	ds_write_b128 v150, v[56:59]
	ds_write_b128 v150, v[52:55] offset:17408
	ds_write_b16 v151, v52 offset:34816
	ds_write_b16_d16_hi v152, v52 offset:34960
	ds_write_b16 v151, v53 offset:35104
	ds_write_b16_d16_hi v151, v53 offset:35248
	ds_write_b16 v151, v54 offset:35392
	ds_write_b16_d16_hi v151, v54 offset:35536
	ds_write_b16 v151, v55 offset:35680
	ds_write_b16_d16_hi v151, v55 offset:35824
	ds_write_b128 v153, v[64:67]
	ds_write_b128 v153, v[68:71] offset:17408
	ds_write_b16 v154, v68 offset:34816
	ds_write_b16_d16_hi v155, v68 offset:34960
	ds_write_b16 v154, v69 offset:35104
	ds_write_b16_d16_hi v154, v69 offset:35248
	ds_write_b16 v154, v70 offset:35392
	ds_write_b16_d16_hi v154, v70 offset:35536
	ds_write_b16 v154, v71 offset:35680
	ds_write_b16_d16_hi v154, v71 offset:35824
	ds_write_b128 v156, v[72:75]
	ds_write_b128 v156, v[76:79] offset:17408
	ds_write_b16 v157, v76 offset:34816
	ds_write_b16_d16_hi v158, v76 offset:34960
	ds_write_b16 v157, v77 offset:35104
	ds_write_b16_d16_hi v157, v77 offset:35248
	ds_write_b16 v157, v78 offset:35392
	ds_write_b16_d16_hi v157, v78 offset:35536
	ds_write_b16 v157, v79 offset:35680
	ds_write_b16_d16_hi v157, v79 offset:35824
	ds_write_b16 v159, v80 offset:53248
	ds_write_b16_d16_hi v160, v80 offset:53392
	ds_write_b16 v159, v81 offset:53536
	ds_write_b16_d16_hi v159, v81 offset:53680
	ds_write_b16 v159, v82 offset:53824
	ds_write_b16_d16_hi v159, v82 offset:53968
	ds_write_b16 v159, v83 offset:54112
	ds_write_b16_d16_hi v159, v83 offset:54256
	s_waitcnt lgkmcnt(0)
	s_barrier
	s_and_saveexec_b64 s[12:13], s[80:81]
	s_cbranch_execz .LBB0_1638
	v_add_u32_e32 v8, s92, v203
	v_ashrrev_i32_e32 v9, 31, v8
	v_lshlrev_b64 v[14:15], 11, v[8:9]
	v_lshl_add_u64 v[14:15], v[138:139], 0, v[14:15]
	global_store_dwordx2 v[14:15], v[4:5], off
	global_store_dwordx2 v[14:15], v[6:7], off offset:32
	s_and_b64 exec, exec, s[44:45]
	s_cbranch_execz .LBB0_1638
	v_lshlrev_b64 v[4:5], 7, v[8:9]
	v_lshl_add_u64 v[4:5], s[6:7], 0, v[4:5]
	global_store_dword v[4:5], v10, off
; __device__ __forceinline__ void gla_unit(const Params& p, const WS& ws, int u, bool dry = false) {
;     ...
;   auto prefetch = [&](int c, u32x4 (&qr)[4], u32x4 (&kr)[4], u32x4& vr, float (&ebl)[2]) {
;     const int tbase = 64 * c - 48;
; #pragma unroll
;     for (int i = 0; i < 4; ++i) {
;       const int ci = tid + 256 * i; const int row = ci >> 4, ch = ci & 15; const int t = tbase + row;
;       qr[i] = (u32x4){0, 0, 0, 0}; kr[i] = (u32x4){0, 0, 0, 0};
;       if (t >= 0) {
;         qr[i] = *(const u32x4*)(ws.Q + (size_t)(b * T_ + t) * 512 + hd * 128 + ch * 8);
;         kr[i] = *(const u32x4*)(ws.K + (size_t)(b * T_ + t) * 512 + hd * 128 + ch * 8);
;       }
;     }
;     {
;       const int row = tid >> 2, ch = tid & 3; const int t = tbase + row;
;       vr = (u32x4){0, 0, 0, 0};
;       if (t >= 0) vr = *(const u32x4*)(ws.V + (size_t)(b * T_ + t) * 1024 + hd * 256 + sl * 32 + ch * 8);
;     }
;     ebl[0] = BLp[c * 128 + 16 * (2 * w) + lr];
;     ebl[1] = BLp[c * 128 + 16 * (2 * w + 1) + lr];
;   };
.LBB0_1638:
	s_or_b64 exec, exec, s[12:13]
	s_cmp_gt_u32 s35, 30
	s_waitcnt vmcnt(11)
	v_mov_b32_e32 v179, v242
	v_mov_b32_e32 v204, v209
	v_mov_b32_e32 v242, v179
	v_mov_b32_e32 v209, v204
	s_cbranch_scc1 .Lgla_skipB
	v_add_u32_e32 v4, s92, v131
	v_mov_b32_e32 v14, v12
	v_mov_b32_e32 v15, v12
	v_mov_b32_e32 v52, v12
	v_mov_b32_e32 v53, v12
	v_add_u32_e32 v4, 0x90, v4
	v_mov_b32_e32 v13, v12
	v_mov_b32_e32 v54, v12
	v_mov_b32_e32 v55, v12
	v_mov_b64_e32 v[48:49], v[52:53]
	v_mov_b64_e32 v[46:47], v[14:15]
	v_cmp_lt_i32_e64 s[80:81], -1, v4
	v_mov_b64_e32 v[50:51], v[54:55]
	v_mov_b64_e32 v[44:45], v[12:13]
	s_and_saveexec_b64 s[12:13], s[80:81]
	s_cbranch_execz .LBB0_1641
	v_add_u32_e32 v4, s92, v202
	v_add_u32_e32 v4, 0x90, v4
	v_ashrrev_i32_e32 v5, 31, v4
	v_lshlrev_b64 v[4:5], 10, v[4:5]
	v_lshl_add_u64 v[6:7], v[132:133], 0, v[4:5]
	v_lshl_add_u64 v[4:5], v[134:135], 0, v[4:5]
	global_load_dwordx4 v[44:47], v[6:7], off
	global_load_dwordx4 v[48:51], v[4:5], off

; __device__ __forceinline__ void gla_unit(const Params& p, const WS& ws, int u, bool dry = false) {
;     ...
; #pragma unroll 1
;   for (int c = 0; c < 33; c += 2) {
;     body(c, qrA, krA, vrA, eblA);
;     if (c + 1 < 33) body(c + 1, qrB, krB, vrB, eblB);
;   }
.LBB0_1664:
	s_add_i32 s37, s37, 2
	s_addk_i32 s92, 0x80
	s_add_i32 s35, s35, 2
	s_cmp_gt_u32 s8, 30
	s_mov_b64 s[8:9], 0x400
	v_lshl_add_u64 v[140:141], v[140:141], 0, s[8:9]
	s_cbranch_scc1 .LBB0_1666
	s_waitcnt vmcnt(11)
	v_mov_b32_e32 v207, v206
	v_mov_b32_e32 v208, v205
	s_branch .LBB0_1607
.Lgla_skipB:
	s_waitcnt vmcnt(0)
	s_branch .LBB0_1650
.Lgla_skipA:
	s_waitcnt vmcnt(0)
	s_branch .LBB0_1622
